# st loop v2 + s_setprio 2 during the intra-chunk loop
# speedup vs baseline: 1.0223x; 1.0115x over previous
.LBB0_818:
	v_mov_b32_e32 v16, v155
	s_or_b32 s6, s37, s9
	v_and_b32_e32 v17, 31, v16
	v_lshrrev_b32_e32 v16, 3, v16
	s_add_i32 s6, s6, s27
	v_and_b32_e32 v16, 0x1ffffc, v16
	v_add_u32_e32 v16, s6, v16
	v_mul_lo_u32 v16, v16, s18
	v_or3_b32 v16, v16, v17, s28
	v_lshlrev_b32_e32 v16, 1, v16
	v_add_u32_e32 v17, 0x3000, v16
	v_add_u32_e32 v18, 0x6000, v16
	v_add_u32_e32 v19, 0x9000, v16
	v_add_u32_e32 v20, 0x18000, v16
	v_add_u32_e32 v21, 0x1b000, v16
	v_add_u32_e32 v22, 0x1e000, v16
	v_add_u32_e32 v23, 0x21000, v16
	global_load_ushort v175, v16, s[4:5]
	global_load_ushort v174, v17, s[4:5]
	global_load_ushort v173, v18, s[4:5]
	global_load_ushort v172, v19, s[4:5]
	global_load_ushort v171, v20, s[4:5]
	global_load_ushort v170, v21, s[4:5]
	global_load_ushort v169, v22, s[4:5]
	global_load_ushort v168, v23, s[4:5]
	v_add_u32_e32 v17, 0x30000, v16
	v_add_u32_e32 v18, 0x33000, v16
	v_add_u32_e32 v19, 0x36000, v16
	v_add_u32_e32 v20, 0x39000, v16
	v_add_u32_e32 v21, 0x48000, v16
	v_add_u32_e32 v22, 0x4b000, v16
	v_add_u32_e32 v23, 0x4e000, v16
	v_add_u32_e32 v16, 0x51000, v16
	global_load_ushort v167, v17, s[4:5]
	global_load_ushort v166, v18, s[4:5]
	global_load_ushort v165, v19, s[4:5]
	global_load_ushort v164, v20, s[4:5]
	global_load_ushort v163, v21, s[4:5]
	global_load_ushort v162, v22, s[4:5]
	global_load_ushort v146, v23, s[4:5]
	global_load_ushort v51, v16, s[4:5]
	v_mov_b32_e32 v17, v155
	v_mov_b32_e32 v16, s36
	s_waitcnt lgkmcnt(0)
	s_barrier
	ds_read_b32 v16, v16 offset:2044
	v_and_b32_e32 v32, 31, v17
	v_or_b32_e32 v176, s27, v32
	v_mul_lo_u32 v18, v176, s20
	v_ashrrev_i32_e32 v34, 5, v17
	v_lshlrev_b32_e32 v177, 4, v34
	v_add_u32_e32 v18, 0, v18
	s_mov_b32 s7, 0x15400
	v_add3_u32 v37, v18, v177, s7
	ds_read_b128 v[112:115], v37
	s_waitcnt lgkmcnt(1)
	v_pk_mul_f32 v[14:15], v[14:15], v[16:17] op_sel_hi:[1,0]
	v_pk_mul_f32 v[12:13], v[12:13], v[16:17] op_sel_hi:[1,0]
	v_pk_mul_f32 v[10:11], v[10:11], v[16:17] op_sel_hi:[1,0]
	v_pk_mul_f32 v[8:9], v[8:9], v[16:17] op_sel_hi:[1,0]
	v_pk_mul_f32 v[6:7], v[6:7], v[16:17] op_sel_hi:[1,0]
	v_pk_mul_f32 v[4:5], v[4:5], v[16:17] op_sel_hi:[1,0]
	v_pk_mul_f32 v[2:3], v[2:3], v[16:17] op_sel_hi:[1,0]
	v_pk_mul_f32 v[0:1], v[0:1], v[16:17] op_sel_hi:[1,0]
	v_or_b32_e32 v16, s23, v32
	v_lshrrev_b32_e32 v47, 1, v17
	v_mul_lo_u32 v16, v16, s20
	v_add_u32_e32 v207, 0, v16
	v_xor_b32_e32 v16, v34, v47
	v_or_b32_e32 v33, s22, v32
	v_lshlrev_b32_e32 v16, 4, v16
	v_mad_u32_u24 v35, v33, s20, 0
	s_mov_b32 s7, 0x1dc00
	v_lshlrev_b32_e32 v36, 3, v34
	v_and_b32_e32 v16, 0xf0, v16
	v_add3_u32 v46, v35, v177, s7
	v_add_u32_e32 v210, v35, v16
	v_bitop3_b32 v16, v36, v32, s23 bitop3:0x1e
	ds_read_b128 v[116:119], v37 offset:32
	v_lshlrev_b32_e32 v20, 1, v16
	ds_read_b128 v[16:19], v46
	v_and_b32_e32 v20, 0xf0, v20
	v_add_u32_e32 v42, v207, v20
	s_waitcnt lgkmcnt(0)
	v_mfma_f32_32x32x16_bf16 v[16:31], v[112:115], v[16:19], 0
	ds_read_b128 v[38:41], v46 offset:32
	ds_read_b128 v[120:123], v37 offset:224
	v_add_u32_e32 v124, 16, v36
	v_lshrrev_b32_e32 v43, 3, v124
	v_xor_b32_e32 v43, v43, v47
	v_lshlrev_b32_e32 v43, 4, v43
	v_and_b32_e32 v43, 0xf0, v43
	v_bitop3_b32 v124, v124, v32, s23 bitop3:0x1e
	s_waitcnt lgkmcnt(1)
	v_mfma_f32_32x32x16_bf16 v[16:31], v[116:119], v[38:41], v[16:31]
	v_add_u32_e32 v125, v35, v43
	v_lshlrev_b32_e32 v124, 1, v124
	ds_read_b128 v[42:45], v42 offset:52224
	ds_read_b128 v[178:181], v125
	v_and_b32_e32 v132, 0xf0, v124
	ds_read_b128 v[124:127], v37 offset:64
	ds_read_b128 v[128:131], v46 offset:64
	v_add_u32_e32 v38, v207, v132
	v_add_u32_e32 v132, 32, v36
	v_lshrrev_b32_e32 v39, 3, v132
	v_xor_b32_e32 v39, v39, v47
	s_waitcnt lgkmcnt(0)
	v_mfma_f32_32x32x16_bf16 v[16:31], v[124:127], v[128:131], v[16:31]
	v_lshlrev_b32_e32 v39, 4, v39
	v_and_b32_e32 v39, 0xf0, v39
	v_add_u32_e32 v133, v35, v39
	ds_read_b128 v[128:131], v37 offset:96
	ds_read_b128 v[38:41], v38 offset:52224
	ds_read_b128 v[182:185], v133
	ds_read_b128 v[136:139], v46 offset:96
	v_bitop3_b32 v132, v132, v32, s23 bitop3:0x1e
	v_lshlrev_b32_e32 v132, 1, v132
	s_waitcnt lgkmcnt(0)
	v_mfma_f32_32x32x16_bf16 v[16:31], v[128:131], v[136:139], v[16:31]
	v_and_b32_e32 v186, 0xf0, v132
	ds_read_b128 v[132:135], v37 offset:128
	ds_read_b128 v[140:143], v46 offset:128
	v_add_u32_e32 v198, 48, v36
	v_lshrrev_b32_e32 v136, 3, v198
	v_xor_b32_e32 v136, v136, v47
	v_lshlrev_b32_e32 v136, 4, v136
	v_add_u32_e32 v190, v207, v186
	v_and_b32_e32 v186, 0xf0, v136
	ds_read_b128 v[136:139], v37 offset:160
	s_waitcnt lgkmcnt(1)
	v_mfma_f32_32x32x16_bf16 v[16:31], v[132:135], v[140:143], v[16:31]
	v_add_u32_e32 v140, v35, v186
	ds_read_b128 v[186:189], v46 offset:160
	ds_read_b128 v[190:193], v190 offset:52224
	ds_read_b128 v[194:197], v140
	v_bitop3_b32 v211, v198, v32, s23 bitop3:0x1e
	ds_read_b128 v[140:143], v37 offset:192
	ds_read_b128 v[198:201], v46 offset:192
	v_add_u32_e32 v218, 64, v36
	v_lshlrev_b32_e32 v37, 1, v211
	v_and_b32_e32 v37, 0xf0, v37
	s_waitcnt lgkmcnt(4)
	v_mfma_f32_32x32x16_bf16 v[16:31], v[136:139], v[186:189], v[16:31]
	v_lshrrev_b32_e32 v186, 3, v218
	v_xor_b32_e32 v186, v186, v47
	v_lshlrev_b32_e32 v186, 4, v186
	v_and_b32_e32 v211, 0xf0, v186
	v_add_u32_e32 v37, v207, v37
	s_lshl_b32 s7, s27, 2
	s_add_i32 s7, s36, s7
	s_waitcnt lgkmcnt(0)
	v_mfma_f32_32x32x16_bf16 v[16:31], v[140:143], v[198:201], v[16:31]
	ds_read_b128 v[186:189], v210
	ds_read_b128 v[198:201], v46 offset:224
	v_add_u32_e32 v46, v35, v211
	ds_read_b128 v[210:213], v37 offset:52224
	ds_read_b128 v[214:217], v46
	v_add_u32_e32 v46, 0x50, v36
	v_bitop3_b32 v37, v218, v32, s23 bitop3:0x1e
	v_lshlrev_b32_e32 v37, 1, v37
	v_and_b32_e32 v37, 0xf0, v37
	s_waitcnt lgkmcnt(3)
	v_mfma_f32_32x32x16_bf16 v[0:15], v[186:189], v[42:45], v[0:15]
	v_add_u32_e32 v37, v207, v37
	s_andn2_b64 vcc, exec, s[50:51]
	v_mfma_f32_32x32x16_bf16 v[0:15], v[178:181], v[38:41], v[0:15]
	v_mfma_f32_32x32x16_bf16 v[0:15], v[182:185], v[190:193], v[0:15]
	s_waitcnt lgkmcnt(2)
	v_mfma_f32_32x32x16_bf16 v[16:31], v[120:123], v[198:201], v[16:31]
	v_lshrrev_b32_e32 v198, 3, v46
	v_xor_b32_e32 v198, v198, v47
	v_lshlrev_b32_e32 v198, 4, v198
	v_and_b32_e32 v42, 0xf0, v198
	v_add_u32_e32 v186, v35, v42
	ds_read_b128 v[42:45], v37 offset:52224
	ds_read_b128 v[186:189], v186
	v_bitop3_b32 v37, v46, v32, s23 bitop3:0x1e
	s_waitcnt lgkmcnt(3)
	v_mfma_f32_32x32x16_bf16 v[0:15], v[194:197], v[210:213], v[0:15]
	v_add_u32_e32 v46, 0x60, v36
	v_lshrrev_b32_e32 v38, 3, v46
	v_xor_b32_e32 v38, v38, v47
	v_lshlrev_b32_e32 v37, 1, v37
	v_lshlrev_b32_e32 v38, 4, v38
	v_and_b32_e32 v37, 0xf0, v37
	v_and_b32_e32 v38, 0xf0, v38
	s_waitcnt lgkmcnt(1)
	v_mfma_f32_32x32x16_bf16 v[0:15], v[214:217], v[42:45], v[0:15]
	v_add_u32_e32 v37, v207, v37
	v_add_u32_e32 v178, v35, v38
	ds_read_b128 v[38:41], v37 offset:52224
	ds_read_b128 v[178:181], v178
	v_bitop3_b32 v37, v46, v32, s23 bitop3:0x1e
	v_add_u32_e32 v46, 0x70, v36
	v_lshrrev_b32_e32 v182, 3, v46
	v_lshlrev_b32_e32 v37, 1, v37
	s_waitcnt lgkmcnt(1)
	v_mfma_f32_32x32x16_bf16 v[0:15], v[186:189], v[38:41], v[0:15]
	v_xor_b32_e32 v47, v182, v47
	v_and_b32_e32 v37, 0xf0, v37
	v_lshlrev_b32_e32 v47, 4, v47
	v_add_u32_e32 v37, v207, v37
	v_and_b32_e32 v47, 0xf0, v47
	v_add_u32_e32 v47, v35, v47
	ds_read_b128 v[182:185], v37 offset:52224
	ds_read_b128 v[190:193], v47
	s_waitcnt lgkmcnt(1)
	v_mfma_f32_32x32x16_bf16 v[0:15], v[178:181], v[182:185], v[0:15]
	v_bitop3_b32 v37, v46, v32, s23 bitop3:0x1e
	v_lshlrev_b32_e32 v37, 1, v37
	v_and_b32_e32 v37, 0xf0, v37
	v_add_u32_e32 v46, s7, v177
	v_add_u32_e32 v37, v207, v37
	ds_read_b128 v[42:45], v46 offset:1632
	ds_read_b128 v[38:41], v46 offset:1568
	ds_read_b128 v[186:189], v46 offset:1600
	ds_read_b128 v[194:197], v37 offset:52224
	ds_read_b128 v[198:201], v46 offset:1536
	s_waitcnt lgkmcnt(1)
	v_mfma_f32_32x32x16_bf16 v[0:15], v[190:193], v[194:197], v[0:15]
	v_mul_f32_e64 v30, v30, v44
	v_mul_f32_e64 v31, v31, v45
	v_mul_f32_e64 v28, v28, v42
	v_mul_f32_e64 v29, v29, v43
	v_mul_f32_e64 v26, v26, v188
	v_mul_f32_e64 v27, v27, v189
	v_pk_mul_f32 v[24:25], v[24:25], v[186:187]
	v_pk_mul_f32 v[22:23], v[22:23], v[40:41]
	v_pk_mul_f32 v[20:21], v[20:21], v[38:39]
	s_waitcnt lgkmcnt(0)
	v_pk_mul_f32 v[18:19], v[18:19], v[200:201]
	v_pk_mul_f32 v[16:17], v[16:17], v[198:199]
	s_cbranch_vccnz .LBB0_821
	v_lshl_add_u32 v37, v176, 2, s36
	ds_read_b32 v178, v37
	v_cndmask_b32_e64 v37, 0, 1, s[52:53]
	v_lshrrev_b32_e32 v181, 1, v33
	v_and_b32_e32 v33, 8, v36
	s_add_i32 s7, 0, 0x4400
	v_lshlrev_b32_e32 v37, 11, v37
	v_add_u32_e32 v182, v35, v33
	v_mov_b32_e32 v33, s7
	v_add_u32_e32 v179, 0, v37
	v_lshlrev_b32_e32 v180, 2, v34
	v_mad_u32_u24 v183, v32, s20, v33
	s_mov_b32 s7, s34
	s_setprio 2
	v_add_u32_e32 v183, v183, v177
	v_add_u32_e32 v179, v179, v177
	v_add_u32_e32 v179, 0x22000, v179
	ds_read_b128 v[96:99], v183 offset:0
	ds_read_b128 v[100:103], v183 offset:32
	ds_read_b128 v[104:107], v183 offset:64
	ds_read_b128 v[108:111], v183 offset:96

.Lst_diag:
	ds_read_b128 v[246:249], v179 offset:0
	ds_read_b128 v[184:187], v179 offset:512
	ds_read_b64 v[196:197], v179 offset:32
	ds_read_b64 v[250:251], v179 offset:40
	ds_read_b128 v[188:191], v179 offset:544
	v_lshrrev_b32_e32 v177, 3, v180
	s_waitcnt lgkmcnt(8)
	v_mfma_f32_32x32x16_bf16 v[32:47], v[96:99], v[112:115], 0
	ds_read_b128 v[96:99], v183 offset:128
	v_cmp_le_i32_e32 vcc, v180, v176
	s_waitcnt lgkmcnt(5)
	v_sub_f32_e32 v246, v178, v246
	v_mul_f32_e32 v246, 0x3fb8aa3b, v246
	v_cndmask_b32_e32 v246, v239, v246, vcc
	v_exp_f32_e32 v246, v246
	v_add_u32_e32 v241, 1, v180
	v_mfma_f32_32x32x16_bf16 v[32:47], v[100:103], v[116:119], v[32:47]
	ds_read_b128 v[100:103], v183 offset:160
	v_cmp_le_i32_e32 vcc, v241, v176
	s_waitcnt lgkmcnt(5)
	v_mul_f32_e32 v184, v184, v246
	v_sub_f32_e32 v247, v178, v247
	v_mul_f32_e32 v247, 0x3fb8aa3b, v247
	v_cndmask_b32_e32 v247, v239, v247, vcc
	v_exp_f32_e32 v247, v247
	v_mfma_f32_32x32x16_bf16 v[32:47], v[104:107], v[124:127], v[32:47]
	ds_read_b128 v[104:107], v183 offset:192
	v_add_u32_e32 v241, 2, v180
	v_cmp_le_i32_e32 vcc, v241, v176
	v_mul_f32_e32 v185, v185, v247
	v_sub_f32_e32 v248, v178, v248
	v_mul_f32_e32 v248, 0x3fb8aa3b, v248
	v_cndmask_b32_e32 v248, v239, v248, vcc
	v_mfma_f32_32x32x16_bf16 v[32:47], v[108:111], v[128:131], v[32:47]
	ds_read_b128 v[108:111], v183 offset:224
	v_exp_f32_e32 v248, v248
	v_add_u32_e32 v241, 3, v180
	v_cmp_le_i32_e32 vcc, v241, v176
	v_mul_f32_e32 v186, v186, v248
	v_sub_f32_e32 v249, v178, v249
	v_mul_f32_e32 v249, 0x3fb8aa3b, v249
	s_waitcnt lgkmcnt(3)
	v_mfma_f32_32x32x16_bf16 v[32:47], v[96:99], v[132:135], v[32:47]
	v_xor_b32_e32 v96, v177, v181
	v_and_b32_e32 v96, 15, v96
	v_lshl_add_u32 v96, v96, 4, v182
	v_add_u32_e32 v98, 1, v177
	v_xor_b32_e32 v98, v98, v181
	v_and_b32_e32 v98, 15, v98
	v_lshl_add_u32 v98, v98, 4, v182
	ds_read_b64 v[96:97], v96
	ds_read_b64 v[98:99], v98
	v_cndmask_b32_e32 v249, v239, v249, vcc
	v_exp_f32_e32 v249, v249
	v_add_u32_e32 v241, 8, v180
	v_cmp_le_i32_e32 vcc, v241, v176
	v_mul_f32_e32 v187, v187, v249
	ds_read_b128 v[246:249], v179 offset:64
	ds_read_b128 v[192:195], v179 offset:576
	v_sub_f32_e32 v196, v178, v196
	s_waitcnt lgkmcnt(6)
	v_mfma_f32_32x32x16_bf16 v[32:47], v[100:103], v[136:139], v[32:47]
	v_add_u32_e32 v100, 2, v177
	v_xor_b32_e32 v100, v100, v181
	v_and_b32_e32 v100, 15, v100
	v_lshl_add_u32 v100, v100, 4, v182
	v_add_u32_e32 v102, 3, v177
	v_xor_b32_e32 v102, v102, v181
	v_and_b32_e32 v102, 15, v102
	v_lshl_add_u32 v102, v102, 4, v182
	ds_read_b64 v[100:101], v100
	ds_read_b64 v[102:103], v102
	v_mul_f32_e32 v196, 0x3fb8aa3b, v196
	v_cndmask_b32_e32 v196, v239, v196, vcc
	v_exp_f32_e32 v196, v196
	v_add_u32_e32 v241, 9, v180
	v_cmp_le_i32_e32 vcc, v241, v176
	v_mul_f32_e32 v188, v188, v196
	s_waitcnt lgkmcnt(7)
	v_mfma_f32_32x32x16_bf16 v[32:47], v[104:107], v[140:143], v[32:47]
	v_sub_f32_e32 v197, v178, v197
	v_mul_f32_e32 v197, 0x3fb8aa3b, v197
	v_cndmask_b32_e32 v197, v239, v197, vcc
	v_exp_f32_e32 v197, v197
	v_add_u32_e32 v241, 10, v180
	v_cmp_le_i32_e32 vcc, v241, v176
	s_waitcnt lgkmcnt(6)
	v_mfma_f32_32x32x16_bf16 v[32:47], v[108:111], v[120:123], v[32:47]
	v_mul_f32_e32 v189, v189, v197
	v_sub_f32_e32 v250, v178, v250
	v_mul_f32_e32 v250, 0x3fb8aa3b, v250
	v_cndmask_b32_e32 v250, v239, v250, vcc
	v_exp_f32_e32 v250, v250
	v_add_u32_e32 v241, 11, v180
	v_cmp_le_i32_e32 vcc, v241, v176
	v_mul_f32_e32 v190, v190, v250
	v_sub_f32_e32 v251, v178, v251
	v_mul_f32_e32 v251, 0x3fb8aa3b, v251
	v_cndmask_b32_e32 v251, v239, v251, vcc
	v_exp_f32_e32 v251, v251
	v_add_u32_e32 v241, 16, v180
	v_cmp_le_i32_e32 vcc, v241, v176
	v_mul_f32_e32 v191, v191, v251
	ds_read_b64 v[196:197], v179 offset:96
	ds_read_b64 v[250:251], v179 offset:104
	ds_read_b128 v[242:245], v179 offset:608
	s_waitcnt lgkmcnt(6)
	v_sub_f32_e32 v246, v178, v246
	v_mul_f32_e32 v246, 0x3fb8aa3b, v246
	v_cndmask_b32_e32 v246, v239, v246, vcc
	v_exp_f32_e32 v246, v246
	v_add_u32_e32 v241, 17, v180
	v_cmp_le_i32_e32 vcc, v241, v176
	s_waitcnt lgkmcnt(5)
	v_mul_f32_e32 v192, v192, v246
	v_sub_f32_e32 v247, v178, v247
	v_mul_f32_e32 v247, 0x3fb8aa3b, v247
	v_cndmask_b32_e32 v247, v239, v247, vcc
	v_exp_f32_e32 v247, v247
	v_add_u32_e32 v241, 18, v180
	v_cmp_le_i32_e32 vcc, v241, v176
	v_mul_f32_e32 v193, v193, v247
	v_sub_f32_e32 v248, v178, v248
	v_mul_f32_e32 v248, 0x3fb8aa3b, v248
	v_cndmask_b32_e32 v248, v239, v248, vcc
	v_exp_f32_e32 v248, v248
	v_add_u32_e32 v241, 19, v180
	v_cmp_le_i32_e32 vcc, v241, v176
	v_mul_f32_e32 v194, v194, v248
	v_sub_f32_e32 v249, v178, v249
	v_mul_f32_e32 v249, 0x3fb8aa3b, v249
	v_cndmask_b32_e32 v249, v239, v249, vcc
	v_exp_f32_e32 v249, v249
	v_add_u32_e32 v241, 24, v180
	v_cmp_le_i32_e32 vcc, v241, v176
	v_mul_f32_e32 v195, v195, v249
	s_waitcnt lgkmcnt(1)
	v_sub_f32_e32 v196, v178, v196
	v_mul_f32_e32 v196, 0x3fb8aa3b, v196
	v_cndmask_b32_e32 v196, v239, v196, vcc
	v_exp_f32_e32 v196, v196
	v_add_u32_e32 v241, 25, v180
	v_cmp_le_i32_e32 vcc, v241, v176
	s_waitcnt lgkmcnt(0)
	v_mul_f32_e32 v242, v242, v196
	v_sub_f32_e32 v197, v178, v197
	v_mul_f32_e32 v197, 0x3fb8aa3b, v197
	v_cndmask_b32_e32 v197, v239, v197, vcc
	v_exp_f32_e32 v197, v197
	v_add_u32_e32 v241, 26, v180
	v_cmp_le_i32_e32 vcc, v241, v176
	v_mul_f32_e32 v243, v243, v197
	v_sub_f32_e32 v250, v178, v250
	v_mul_f32_e32 v250, 0x3fb8aa3b, v250
	v_cndmask_b32_e32 v250, v239, v250, vcc
	v_exp_f32_e32 v250, v250
	v_add_u32_e32 v241, 27, v180
	v_cmp_le_i32_e32 vcc, v241, v176
	v_mul_f32_e32 v244, v244, v250
	v_sub_f32_e32 v251, v178, v251
	v_mul_f32_e32 v251, 0x3fb8aa3b, v251
	v_cndmask_b32_e32 v251, v239, v251, vcc
	v_exp_f32_e32 v251, v251
	s_nop 0
	v_mul_f32_e32 v245, v245, v251
	v_mul_f32_e32 v32, v32, v184
	v_mul_f32_e32 v33, v33, v185
	v_mul_f32_e32 v34, v34, v186
	v_mul_f32_e32 v35, v35, v187
	v_mul_f32_e32 v36, v36, v188
	v_mul_f32_e32 v37, v37, v189
	v_mul_f32_e32 v38, v38, v190
	v_mul_f32_e32 v39, v39, v191
	v_mul_f32_e32 v40, v40, v192
	v_mul_f32_e32 v41, v41, v193
	v_mul_f32_e32 v42, v42, v194
	v_mul_f32_e32 v43, v43, v195
	v_mul_f32_e32 v44, v44, v242
	v_mul_f32_e32 v45, v45, v243
	v_mul_f32_e32 v46, v46, v244
	v_mul_f32_e32 v47, v47, v245
	v_cvt_pk_bf16_f32 v32, v32, v33
	v_cvt_pk_bf16_f32 v33, v34, v35
	v_cvt_pk_bf16_f32 v34, v36, v37
	v_cvt_pk_bf16_f32 v35, v38, v39
	v_cvt_pk_bf16_f32 v36, v40, v41
	v_cvt_pk_bf16_f32 v37, v42, v43
	v_cvt_pk_bf16_f32 v38, v44, v45
	v_cvt_pk_bf16_f32 v39, v46, v47
	v_add_u32_e32 v183, 0x2200, v183
	v_add_u32_e32 v179, 0x80, v179
	v_mfma_f32_32x32x16_bf16 v[16:31], v[32:35], v[96:99], v[16:31]
	v_add_u32_e32 v180, 32, v180
	v_mfma_f32_32x32x16_bf16 v[16:31], v[36:39], v[100:103], v[16:31]
	s_setprio 0
